# transpose-norm phase: per-wave token loop batched (2-token steps, b32 LDS reads prefetched, 4 sums reduced together by DPP + 2 bpermute rounds, gain loads waited late)
# speedup vs baseline: 1.0019x; 1.0019x over previous
.LBB0_197:
	s_lshl_b32 s0, s9, 6
	s_ashr_i32 s1, s0, 31
	v_lshl_add_u64 v[126:127], s[0:1], 1, v[0:1]
	v_lshl_add_u64 v[40:41], v[126:127], 0, v[2:3]
	s_waitcnt vmcnt(0)
	s_barrier
	global_load_dwordx4 v[40:43], v[40:41], off nt
	v_lshl_add_u64 v[44:45], v[126:127], 0, v[4:5]
	global_load_dwordx4 v[44:47], v[44:45], off nt
	v_lshl_add_u64 v[48:49], v[126:127], 0, v[6:7]
	global_load_dwordx4 v[48:51], v[48:49], off nt
	v_lshl_add_u64 v[52:53], v[126:127], 0, v[8:9]
	global_load_dwordx4 v[52:55], v[52:53], off nt
	v_lshl_add_u64 v[56:57], v[126:127], 0, v[10:11]
	global_load_dwordx4 v[56:59], v[56:57], off nt
	v_lshl_add_u64 v[60:61], v[126:127], 0, v[12:13]
	global_load_dwordx4 v[60:63], v[60:61], off nt
	v_lshl_add_u64 v[64:65], v[126:127], 0, v[14:15]
	global_load_dwordx4 v[64:67], v[64:65], off nt
	v_lshl_add_u64 v[68:69], v[126:127], 0, v[16:17]
	global_load_dwordx4 v[68:71], v[68:69], off nt
	v_lshl_add_u64 v[98:99], v[126:127], 0, v[18:19]
	global_load_dwordx4 v[98:101], v[98:99], off nt
	v_lshl_add_u64 v[102:103], v[126:127], 0, v[20:21]
	global_load_dwordx4 v[102:105], v[102:103], off nt
	v_lshl_add_u64 v[106:107], v[126:127], 0, v[22:23]
	global_load_dwordx4 v[106:109], v[106:107], off nt
	v_lshl_add_u64 v[110:111], v[126:127], 0, v[24:25]
	global_load_dwordx4 v[110:113], v[110:111], off nt
	v_lshl_add_u64 v[114:115], v[126:127], 0, v[26:27]
	global_load_dwordx4 v[114:117], v[114:115], off nt
	v_lshl_add_u64 v[118:119], v[126:127], 0, v[28:29]
	global_load_dwordx4 v[118:121], v[118:119], off nt
	v_lshl_add_u64 v[122:123], v[126:127], 0, v[30:31]
	global_load_dwordx4 v[122:125], v[122:123], off nt
	v_lshl_add_u64 v[126:127], v[126:127], 0, v[32:33]
	global_load_dwordx4 v[126:129], v[126:127], off nt
	s_mov_b64 s[38:39], 0
	v_mov_b32_e32 v97, v80
	s_waitcnt vmcnt(15)
	ds_write2_b32 v81, v40, v41 offset1:1
	ds_write2_b32 v81, v42, v43 offset0:2 offset1:3
	s_waitcnt vmcnt(14)
	ds_write2_b32 v82, v44, v45 offset1:1
	ds_write2_b32 v82, v46, v47 offset0:2 offset1:3
	s_waitcnt vmcnt(13)
	ds_write2_b32 v83, v48, v49 offset1:1
	ds_write2_b32 v83, v50, v51 offset0:2 offset1:3
	s_waitcnt vmcnt(12)
	ds_write2_b32 v84, v52, v53 offset1:1
	ds_write2_b32 v84, v54, v55 offset0:2 offset1:3
	s_waitcnt vmcnt(11)
	ds_write2_b32 v85, v56, v57 offset1:1
	ds_write2_b32 v85, v58, v59 offset0:2 offset1:3
	s_waitcnt vmcnt(10)
	ds_write2_b32 v86, v60, v61 offset1:1
	ds_write2_b32 v86, v62, v63 offset0:2 offset1:3
	s_waitcnt vmcnt(9)
	ds_write2_b32 v87, v64, v65 offset1:1
	ds_write2_b32 v87, v66, v67 offset0:2 offset1:3
	s_waitcnt vmcnt(8)
	ds_write2_b32 v88, v68, v69 offset1:1
	ds_write2_b32 v88, v70, v71 offset0:2 offset1:3
	s_waitcnt vmcnt(7)
	ds_write2_b32 v89, v98, v99 offset1:1
	ds_write2_b32 v89, v100, v101 offset0:2 offset1:3
	s_waitcnt vmcnt(6)
	ds_write2_b32 v90, v102, v103 offset1:1
	ds_write2_b32 v90, v104, v105 offset0:2 offset1:3
	s_waitcnt vmcnt(5)
	ds_write2_b32 v91, v106, v107 offset1:1
	ds_write2_b32 v91, v108, v109 offset0:2 offset1:3
	s_waitcnt vmcnt(4)
	ds_write2_b32 v92, v110, v111 offset1:1
	ds_write2_b32 v92, v112, v113 offset0:2 offset1:3
	s_waitcnt vmcnt(3)
	ds_write2_b32 v93, v114, v115 offset1:1
	ds_write2_b32 v93, v116, v117 offset0:2 offset1:3
	s_waitcnt vmcnt(2)
	ds_write2_b32 v94, v118, v119 offset1:1
	ds_write2_b32 v94, v120, v121 offset0:2 offset1:3
	s_waitcnt vmcnt(1)
	ds_write2_b32 v95, v122, v123 offset1:1
	ds_write2_b32 v95, v124, v125 offset0:2 offset1:3
	s_waitcnt vmcnt(0)
	ds_write2_b32 v96, v126, v127 offset1:1
	ds_write2_b32 v96, v128, v129 offset0:2 offset1:3
	s_waitcnt lgkmcnt(0)
	s_barrier
	global_load_dwordx2 v[40:41], v[34:35], off
	global_load_dwordx2 v[42:43], v[34:35], off offset:512
	global_load_dwordx2 v[44:45], v[34:35], off offset:1024
	global_load_dwordx2 v[46:47], v[34:35], off offset:1536
	global_load_dwordx2 v[48:49], v[36:37], off
	global_load_dwordx2 v[50:51], v[36:37], off offset:512
	global_load_dwordx2 v[52:53], v[36:37], off offset:1024
	global_load_dwordx2 v[54:55], v[36:37], off offset:1536
	v_readfirstlane_b32 s0, v179
	v_mul_u32_u24_e32 v56, 0x108, v225
	s_lshr_b32 s0, s0, 6
	s_lshl_b32 s1, s0, 4
	s_lshl_b32 s0, s0, 3
	v_add_u32_e32 v56, s1, v56
	s_add_i32 s0, s0, s7
	v_add_u32_e32 v57, 0x10800, v56
	s_lshl_b32 s0, s0, 11
	v_mov_b32_e32 v60, s0
	ds_read_b32 v100, v56 offset:0
	ds_read_b32 v101, v56 offset:132
	ds_read_b32 v102, v56 offset:16896
	ds_read_b32 v103, v56 offset:17028
	ds_read_b32 v104, v56 offset:33792
	ds_read_b32 v105, v56 offset:33924
	ds_read_b32 v106, v56 offset:50688
	ds_read_b32 v107, v56 offset:50820
	ds_read_b32 v108, v57 offset:0
	ds_read_b32 v109, v57 offset:132
	ds_read_b32 v110, v57 offset:16896
	ds_read_b32 v111, v57 offset:17028
	ds_read_b32 v112, v57 offset:33792
	ds_read_b32 v113, v57 offset:33924
	ds_read_b32 v114, v57 offset:50688
	ds_read_b32 v115, v57 offset:50820
	ds_read_b32 v116, v56 offset:4
	ds_read_b32 v117, v56 offset:136
	ds_read_b32 v118, v56 offset:16900
	ds_read_b32 v119, v56 offset:17032
	ds_read_b32 v120, v56 offset:33796
	ds_read_b32 v121, v56 offset:33928
	ds_read_b32 v122, v56 offset:50692
	ds_read_b32 v123, v56 offset:50824
	ds_read_b32 v124, v57 offset:4
	ds_read_b32 v125, v57 offset:136
	ds_read_b32 v126, v57 offset:16900
	ds_read_b32 v127, v57 offset:17032
	ds_read_b32 v128, v57 offset:33796
	ds_read_b32 v129, v57 offset:33928
	ds_read_b32 v130, v57 offset:50692
	ds_read_b32 v131, v57 offset:50824
	s_waitcnt lgkmcnt(15)
	v_lshlrev_b32_e32 v132, 16, v100
	v_lshlrev_b32_e32 v133, 16, v101
	v_and_b32_e32 v100, 0xffff0000, v100
	v_and_b32_e32 v101, 0xffff0000, v101
	v_lshlrev_b32_e32 v134, 16, v102
	v_lshlrev_b32_e32 v135, 16, v103
	v_and_b32_e32 v102, 0xffff0000, v102
	v_and_b32_e32 v103, 0xffff0000, v103
	v_lshlrev_b32_e32 v136, 16, v104
	v_lshlrev_b32_e32 v137, 16, v105
	v_and_b32_e32 v104, 0xffff0000, v104
	v_and_b32_e32 v105, 0xffff0000, v105
	v_lshlrev_b32_e32 v138, 16, v106
	v_lshlrev_b32_e32 v139, 16, v107
	v_and_b32_e32 v106, 0xffff0000, v106
	v_and_b32_e32 v107, 0xffff0000, v107
	v_lshlrev_b32_e32 v140, 16, v108
	v_lshlrev_b32_e32 v141, 16, v109
	v_and_b32_e32 v108, 0xffff0000, v108
	v_and_b32_e32 v109, 0xffff0000, v109
	v_lshlrev_b32_e32 v142, 16, v110
	v_lshlrev_b32_e32 v143, 16, v111
	v_and_b32_e32 v110, 0xffff0000, v110
	v_and_b32_e32 v111, 0xffff0000, v111
	v_lshlrev_b32_e32 v144, 16, v112
	v_lshlrev_b32_e32 v145, 16, v113
	v_and_b32_e32 v112, 0xffff0000, v112
	v_and_b32_e32 v113, 0xffff0000, v113
	v_lshlrev_b32_e32 v146, 16, v114
	v_lshlrev_b32_e32 v147, 16, v115
	v_and_b32_e32 v114, 0xffff0000, v114
	v_and_b32_e32 v115, 0xffff0000, v115
	v_pk_mul_f32 v[152:153], v[132:133], v[132:133]
	v_pk_mul_f32 v[154:155], v[140:141], v[140:141]
	v_pk_mul_f32 v[156:157], v[100:101], v[100:101]
	v_pk_mul_f32 v[158:159], v[108:109], v[108:109]
	v_pk_fma_f32 v[152:153], v[134:135], v[134:135], v[152:153]
	v_pk_fma_f32 v[154:155], v[142:143], v[142:143], v[154:155]
	v_pk_fma_f32 v[156:157], v[102:103], v[102:103], v[156:157]
	v_pk_fma_f32 v[158:159], v[110:111], v[110:111], v[158:159]
	v_pk_fma_f32 v[152:153], v[136:137], v[136:137], v[152:153]
	v_pk_fma_f32 v[154:155], v[144:145], v[144:145], v[154:155]
	v_pk_fma_f32 v[156:157], v[104:105], v[104:105], v[156:157]
	v_pk_fma_f32 v[158:159], v[112:113], v[112:113], v[158:159]
	v_pk_fma_f32 v[152:153], v[138:139], v[138:139], v[152:153]
	v_pk_fma_f32 v[154:155], v[146:147], v[146:147], v[154:155]
	v_pk_fma_f32 v[156:157], v[106:107], v[106:107], v[156:157]
	v_pk_fma_f32 v[158:159], v[114:115], v[114:115], v[158:159]
	v_add_f32_e32 v148, v152, v153
	v_add_f32_e32 v149, v154, v155
	v_add_f32_e32 v150, v156, v157
	v_add_f32_e32 v151, v158, v159
	v_add_u32_e32 v61, 0x0, v60
	s_nop 0
	v_add_f32_dpp v160, v148, v148 quad_perm:[1,0,3,2] row_mask:0xf bank_mask:0xf
	v_add_f32_dpp v161, v149, v149 quad_perm:[1,0,3,2] row_mask:0xf bank_mask:0xf
	v_add_f32_dpp v162, v150, v150 quad_perm:[1,0,3,2] row_mask:0xf bank_mask:0xf
	v_add_f32_dpp v163, v151, v151 quad_perm:[1,0,3,2] row_mask:0xf bank_mask:0xf
	s_nop 0
	v_add_f32_dpp v148, v160, v160 quad_perm:[2,3,0,1] row_mask:0xf bank_mask:0xf
	v_add_f32_dpp v149, v161, v161 quad_perm:[2,3,0,1] row_mask:0xf bank_mask:0xf
	v_add_f32_dpp v150, v162, v162 quad_perm:[2,3,0,1] row_mask:0xf bank_mask:0xf
	v_add_f32_dpp v151, v163, v163 quad_perm:[2,3,0,1] row_mask:0xf bank_mask:0xf
	s_nop 0
	v_add_f32_dpp v160, v148, v148 row_ror:4 row_mask:0xf bank_mask:0xf
	v_add_f32_dpp v161, v149, v149 row_ror:4 row_mask:0xf bank_mask:0xf
	v_add_f32_dpp v162, v150, v150 row_ror:4 row_mask:0xf bank_mask:0xf
	v_add_f32_dpp v163, v151, v151 row_ror:4 row_mask:0xf bank_mask:0xf
	s_nop 0
	v_add_f32_dpp v148, v160, v160 row_ror:8 row_mask:0xf bank_mask:0xf
	v_add_f32_dpp v149, v161, v161 row_ror:8 row_mask:0xf bank_mask:0xf
	v_add_f32_dpp v150, v162, v162 row_ror:8 row_mask:0xf bank_mask:0xf
	v_add_f32_dpp v151, v163, v163 row_ror:8 row_mask:0xf bank_mask:0xf
	ds_bpermute_b32 v160, v74, v148
	ds_bpermute_b32 v161, v74, v149
	ds_bpermute_b32 v162, v74, v150
	ds_bpermute_b32 v163, v74, v151
	s_waitcnt lgkmcnt(0)
	v_add_f32_e32 v148, v148, v160
	v_add_f32_e32 v149, v149, v161
	v_add_f32_e32 v150, v150, v162
	v_add_f32_e32 v151, v151, v163
	ds_bpermute_b32 v160, v73, v148
	ds_bpermute_b32 v161, v73, v149
	ds_bpermute_b32 v162, v73, v150
	ds_bpermute_b32 v163, v73, v151
	s_waitcnt lgkmcnt(0)
	v_add_f32_e32 v148, v148, v160
	v_add_f32_e32 v149, v149, v161
	v_add_f32_e32 v150, v150, v162
	v_add_f32_e32 v151, v151, v163
	v_fma_f32 v148, v148, s4, v178
	v_fma_f32 v149, v149, s4, v178
	v_fma_f32 v150, v150, s4, v178
	v_fma_f32 v151, v151, s4, v178
	v_rsq_f32_e32 v164, v148
	v_rsq_f32_e32 v166, v149
	v_rsq_f32_e32 v168, v150
	v_rsq_f32_e32 v170, v151
	s_waitcnt vmcnt(0)
	v_add_co_u32_e32 v58, vcc, v61, v38
	s_nop 1
	v_addc_co_u32_e32 v59, vcc, 0, v39, vcc
	v_pk_mul_f32 v[132:133], v[132:133], v[164:165] op_sel_hi:[1,0]
	v_pk_mul_f32 v[132:133], v[40:41], v[132:133]
	v_cvt_pk_bf16_f32 v132, v132, v133
	global_store_dword v[58:59], v132, off
	v_pk_mul_f32 v[134:135], v[134:135], v[164:165] op_sel_hi:[1,0]
	v_pk_mul_f32 v[134:135], v[42:43], v[134:135]
	v_cvt_pk_bf16_f32 v134, v134, v135
	global_store_dword v[58:59], v134, off offset:256
	v_pk_mul_f32 v[136:137], v[136:137], v[164:165] op_sel_hi:[1,0]
	v_pk_mul_f32 v[136:137], v[44:45], v[136:137]
	v_cvt_pk_bf16_f32 v136, v136, v137
	global_store_dword v[58:59], v136, off offset:512
	v_pk_mul_f32 v[138:139], v[138:139], v[164:165] op_sel_hi:[1,0]
	v_pk_mul_f32 v[138:139], v[46:47], v[138:139]
	v_cvt_pk_bf16_f32 v138, v138, v139
	global_store_dword v[58:59], v138, off offset:768
	v_pk_mul_f32 v[140:141], v[140:141], v[166:167] op_sel_hi:[1,0]
	v_pk_mul_f32 v[140:141], v[48:49], v[140:141]
	v_cvt_pk_bf16_f32 v140, v140, v141
	global_store_dword v[58:59], v140, off offset:1024
	v_pk_mul_f32 v[142:143], v[142:143], v[166:167] op_sel_hi:[1,0]
	v_pk_mul_f32 v[142:143], v[50:51], v[142:143]
	v_cvt_pk_bf16_f32 v142, v142, v143
	global_store_dword v[58:59], v142, off offset:1280
	v_pk_mul_f32 v[144:145], v[144:145], v[166:167] op_sel_hi:[1,0]
	v_pk_mul_f32 v[144:145], v[52:53], v[144:145]
	v_cvt_pk_bf16_f32 v144, v144, v145
	global_store_dword v[58:59], v144, off offset:1536
	v_pk_mul_f32 v[146:147], v[146:147], v[166:167] op_sel_hi:[1,0]
	v_pk_mul_f32 v[146:147], v[54:55], v[146:147]
	v_cvt_pk_bf16_f32 v146, v146, v147
	global_store_dword v[58:59], v146, off offset:1792
	v_add_u32_e32 v61, 0x800, v61
	v_add_co_u32_e32 v58, vcc, v61, v38
	s_nop 1
	v_addc_co_u32_e32 v59, vcc, 0, v39, vcc
	v_pk_mul_f32 v[100:101], v[100:101], v[168:169] op_sel_hi:[1,0]
	v_pk_mul_f32 v[100:101], v[40:41], v[100:101]
	v_cvt_pk_bf16_f32 v100, v100, v101
	global_store_dword v[58:59], v100, off
	v_pk_mul_f32 v[102:103], v[102:103], v[168:169] op_sel_hi:[1,0]
	v_pk_mul_f32 v[102:103], v[42:43], v[102:103]
	v_cvt_pk_bf16_f32 v102, v102, v103
	global_store_dword v[58:59], v102, off offset:256
	v_pk_mul_f32 v[104:105], v[104:105], v[168:169] op_sel_hi:[1,0]
	v_pk_mul_f32 v[104:105], v[44:45], v[104:105]
	v_cvt_pk_bf16_f32 v104, v104, v105
	global_store_dword v[58:59], v104, off offset:512
	v_pk_mul_f32 v[106:107], v[106:107], v[168:169] op_sel_hi:[1,0]
	v_pk_mul_f32 v[106:107], v[46:47], v[106:107]
	v_cvt_pk_bf16_f32 v106, v106, v107
	global_store_dword v[58:59], v106, off offset:768
	v_pk_mul_f32 v[108:109], v[108:109], v[170:171] op_sel_hi:[1,0]
	v_pk_mul_f32 v[108:109], v[48:49], v[108:109]
	v_cvt_pk_bf16_f32 v108, v108, v109
	global_store_dword v[58:59], v108, off offset:1024
	v_pk_mul_f32 v[110:111], v[110:111], v[170:171] op_sel_hi:[1,0]
	v_pk_mul_f32 v[110:111], v[50:51], v[110:111]
	v_cvt_pk_bf16_f32 v110, v110, v111
	global_store_dword v[58:59], v110, off offset:1280
	v_pk_mul_f32 v[112:113], v[112:113], v[170:171] op_sel_hi:[1,0]
	v_pk_mul_f32 v[112:113], v[52:53], v[112:113]
	v_cvt_pk_bf16_f32 v112, v112, v113
	global_store_dword v[58:59], v112, off offset:1536
	v_pk_mul_f32 v[114:115], v[114:115], v[170:171] op_sel_hi:[1,0]
	v_pk_mul_f32 v[114:115], v[54:55], v[114:115]
	v_cvt_pk_bf16_f32 v114, v114, v115
	global_store_dword v[58:59], v114, off offset:1792
	ds_read_b32 v100, v56 offset:8
	ds_read_b32 v101, v56 offset:140
	ds_read_b32 v102, v56 offset:16904
	ds_read_b32 v103, v56 offset:17036
	ds_read_b32 v104, v56 offset:33800
	ds_read_b32 v105, v56 offset:33932
	ds_read_b32 v106, v56 offset:50696
	ds_read_b32 v107, v56 offset:50828
	ds_read_b32 v108, v57 offset:8
	ds_read_b32 v109, v57 offset:140
	ds_read_b32 v110, v57 offset:16904
	ds_read_b32 v111, v57 offset:17036
	ds_read_b32 v112, v57 offset:33800
	ds_read_b32 v113, v57 offset:33932
	ds_read_b32 v114, v57 offset:50696
	ds_read_b32 v115, v57 offset:50828
	s_waitcnt lgkmcnt(15)
	v_lshlrev_b32_e32 v132, 16, v116
	v_lshlrev_b32_e32 v133, 16, v117
	v_and_b32_e32 v116, 0xffff0000, v116
	v_and_b32_e32 v117, 0xffff0000, v117
	v_lshlrev_b32_e32 v134, 16, v118
	v_lshlrev_b32_e32 v135, 16, v119
	v_and_b32_e32 v118, 0xffff0000, v118
	v_and_b32_e32 v119, 0xffff0000, v119
	v_lshlrev_b32_e32 v136, 16, v120
	v_lshlrev_b32_e32 v137, 16, v121
	v_and_b32_e32 v120, 0xffff0000, v120
	v_and_b32_e32 v121, 0xffff0000, v121
	v_lshlrev_b32_e32 v138, 16, v122
	v_lshlrev_b32_e32 v139, 16, v123
	v_and_b32_e32 v122, 0xffff0000, v122
	v_and_b32_e32 v123, 0xffff0000, v123
	v_lshlrev_b32_e32 v140, 16, v124
	v_lshlrev_b32_e32 v141, 16, v125
	v_and_b32_e32 v124, 0xffff0000, v124
	v_and_b32_e32 v125, 0xffff0000, v125
	v_lshlrev_b32_e32 v142, 16, v126
	v_lshlrev_b32_e32 v143, 16, v127
	v_and_b32_e32 v126, 0xffff0000, v126
	v_and_b32_e32 v127, 0xffff0000, v127
	v_lshlrev_b32_e32 v144, 16, v128
	v_lshlrev_b32_e32 v145, 16, v129
	v_and_b32_e32 v128, 0xffff0000, v128
	v_and_b32_e32 v129, 0xffff0000, v129
	v_lshlrev_b32_e32 v146, 16, v130
	v_lshlrev_b32_e32 v147, 16, v131
	v_and_b32_e32 v130, 0xffff0000, v130
	v_and_b32_e32 v131, 0xffff0000, v131
	v_pk_mul_f32 v[152:153], v[132:133], v[132:133]
	v_pk_mul_f32 v[154:155], v[140:141], v[140:141]
	v_pk_mul_f32 v[156:157], v[116:117], v[116:117]
	v_pk_mul_f32 v[158:159], v[124:125], v[124:125]
	v_pk_fma_f32 v[152:153], v[134:135], v[134:135], v[152:153]
	v_pk_fma_f32 v[154:155], v[142:143], v[142:143], v[154:155]
	v_pk_fma_f32 v[156:157], v[118:119], v[118:119], v[156:157]
	v_pk_fma_f32 v[158:159], v[126:127], v[126:127], v[158:159]
	v_pk_fma_f32 v[152:153], v[136:137], v[136:137], v[152:153]
	v_pk_fma_f32 v[154:155], v[144:145], v[144:145], v[154:155]
	v_pk_fma_f32 v[156:157], v[120:121], v[120:121], v[156:157]
	v_pk_fma_f32 v[158:159], v[128:129], v[128:129], v[158:159]
	v_pk_fma_f32 v[152:153], v[138:139], v[138:139], v[152:153]
	v_pk_fma_f32 v[154:155], v[146:147], v[146:147], v[154:155]
	v_pk_fma_f32 v[156:157], v[122:123], v[122:123], v[156:157]
	v_pk_fma_f32 v[158:159], v[130:131], v[130:131], v[158:159]
	v_add_f32_e32 v148, v152, v153
	v_add_f32_e32 v149, v154, v155
	v_add_f32_e32 v150, v156, v157
	v_add_f32_e32 v151, v158, v159
	v_add_u32_e32 v61, 0x1000, v60
	s_nop 0
	v_add_f32_dpp v160, v148, v148 quad_perm:[1,0,3,2] row_mask:0xf bank_mask:0xf
	v_add_f32_dpp v161, v149, v149 quad_perm:[1,0,3,2] row_mask:0xf bank_mask:0xf
	v_add_f32_dpp v162, v150, v150 quad_perm:[1,0,3,2] row_mask:0xf bank_mask:0xf
	v_add_f32_dpp v163, v151, v151 quad_perm:[1,0,3,2] row_mask:0xf bank_mask:0xf
	s_nop 0
	v_add_f32_dpp v148, v160, v160 quad_perm:[2,3,0,1] row_mask:0xf bank_mask:0xf
	v_add_f32_dpp v149, v161, v161 quad_perm:[2,3,0,1] row_mask:0xf bank_mask:0xf
	v_add_f32_dpp v150, v162, v162 quad_perm:[2,3,0,1] row_mask:0xf bank_mask:0xf
	v_add_f32_dpp v151, v163, v163 quad_perm:[2,3,0,1] row_mask:0xf bank_mask:0xf
	s_nop 0
	v_add_f32_dpp v160, v148, v148 row_ror:4 row_mask:0xf bank_mask:0xf
	v_add_f32_dpp v161, v149, v149 row_ror:4 row_mask:0xf bank_mask:0xf
	v_add_f32_dpp v162, v150, v150 row_ror:4 row_mask:0xf bank_mask:0xf
	v_add_f32_dpp v163, v151, v151 row_ror:4 row_mask:0xf bank_mask:0xf
	s_nop 0
	v_add_f32_dpp v148, v160, v160 row_ror:8 row_mask:0xf bank_mask:0xf
	v_add_f32_dpp v149, v161, v161 row_ror:8 row_mask:0xf bank_mask:0xf
	v_add_f32_dpp v150, v162, v162 row_ror:8 row_mask:0xf bank_mask:0xf
	v_add_f32_dpp v151, v163, v163 row_ror:8 row_mask:0xf bank_mask:0xf
	ds_bpermute_b32 v160, v74, v148
	ds_bpermute_b32 v161, v74, v149
	ds_bpermute_b32 v162, v74, v150
	ds_bpermute_b32 v163, v74, v151
	s_waitcnt lgkmcnt(0)
	v_add_f32_e32 v148, v148, v160
	v_add_f32_e32 v149, v149, v161
	v_add_f32_e32 v150, v150, v162
	v_add_f32_e32 v151, v151, v163
	ds_bpermute_b32 v160, v73, v148
	ds_bpermute_b32 v161, v73, v149
	ds_bpermute_b32 v162, v73, v150
	ds_bpermute_b32 v163, v73, v151
	s_waitcnt lgkmcnt(0)
	v_add_f32_e32 v148, v148, v160
	v_add_f32_e32 v149, v149, v161
	v_add_f32_e32 v150, v150, v162
	v_add_f32_e32 v151, v151, v163
	v_fma_f32 v148, v148, s4, v178
	v_fma_f32 v149, v149, s4, v178
	v_fma_f32 v150, v150, s4, v178
	v_fma_f32 v151, v151, s4, v178
	v_rsq_f32_e32 v164, v148
	v_rsq_f32_e32 v166, v149
	v_rsq_f32_e32 v168, v150
	v_rsq_f32_e32 v170, v151
	v_add_co_u32_e32 v58, vcc, v61, v38
	s_nop 1
	v_addc_co_u32_e32 v59, vcc, 0, v39, vcc
	v_pk_mul_f32 v[132:133], v[132:133], v[164:165] op_sel_hi:[1,0]
	v_pk_mul_f32 v[132:133], v[40:41], v[132:133]
	v_cvt_pk_bf16_f32 v132, v132, v133
	global_store_dword v[58:59], v132, off
	v_pk_mul_f32 v[134:135], v[134:135], v[164:165] op_sel_hi:[1,0]
	v_pk_mul_f32 v[134:135], v[42:43], v[134:135]
	v_cvt_pk_bf16_f32 v134, v134, v135
	global_store_dword v[58:59], v134, off offset:256
	v_pk_mul_f32 v[136:137], v[136:137], v[164:165] op_sel_hi:[1,0]
	v_pk_mul_f32 v[136:137], v[44:45], v[136:137]
	v_cvt_pk_bf16_f32 v136, v136, v137
	global_store_dword v[58:59], v136, off offset:512
	v_pk_mul_f32 v[138:139], v[138:139], v[164:165] op_sel_hi:[1,0]
	v_pk_mul_f32 v[138:139], v[46:47], v[138:139]
	v_cvt_pk_bf16_f32 v138, v138, v139
	global_store_dword v[58:59], v138, off offset:768
	v_pk_mul_f32 v[140:141], v[140:141], v[166:167] op_sel_hi:[1,0]
	v_pk_mul_f32 v[140:141], v[48:49], v[140:141]
	v_cvt_pk_bf16_f32 v140, v140, v141
	global_store_dword v[58:59], v140, off offset:1024
	v_pk_mul_f32 v[142:143], v[142:143], v[166:167] op_sel_hi:[1,0]
	v_pk_mul_f32 v[142:143], v[50:51], v[142:143]
	v_cvt_pk_bf16_f32 v142, v142, v143
	global_store_dword v[58:59], v142, off offset:1280
	v_pk_mul_f32 v[144:145], v[144:145], v[166:167] op_sel_hi:[1,0]
	v_pk_mul_f32 v[144:145], v[52:53], v[144:145]
	v_cvt_pk_bf16_f32 v144, v144, v145
	global_store_dword v[58:59], v144, off offset:1536
	v_pk_mul_f32 v[146:147], v[146:147], v[166:167] op_sel_hi:[1,0]
	v_pk_mul_f32 v[146:147], v[54:55], v[146:147]
	v_cvt_pk_bf16_f32 v146, v146, v147
	global_store_dword v[58:59], v146, off offset:1792
	v_add_u32_e32 v61, 0x800, v61
	v_add_co_u32_e32 v58, vcc, v61, v38
	s_nop 1
	v_addc_co_u32_e32 v59, vcc, 0, v39, vcc
	v_pk_mul_f32 v[116:117], v[116:117], v[168:169] op_sel_hi:[1,0]
	v_pk_mul_f32 v[116:117], v[40:41], v[116:117]
	v_cvt_pk_bf16_f32 v116, v116, v117
	global_store_dword v[58:59], v116, off
	v_pk_mul_f32 v[118:119], v[118:119], v[168:169] op_sel_hi:[1,0]
	v_pk_mul_f32 v[118:119], v[42:43], v[118:119]
	v_cvt_pk_bf16_f32 v118, v118, v119
	global_store_dword v[58:59], v118, off offset:256
	v_pk_mul_f32 v[120:121], v[120:121], v[168:169] op_sel_hi:[1,0]
	v_pk_mul_f32 v[120:121], v[44:45], v[120:121]
	v_cvt_pk_bf16_f32 v120, v120, v121
	global_store_dword v[58:59], v120, off offset:512
	v_pk_mul_f32 v[122:123], v[122:123], v[168:169] op_sel_hi:[1,0]
	v_pk_mul_f32 v[122:123], v[46:47], v[122:123]
	v_cvt_pk_bf16_f32 v122, v122, v123
	global_store_dword v[58:59], v122, off offset:768
	v_pk_mul_f32 v[124:125], v[124:125], v[170:171] op_sel_hi:[1,0]
	v_pk_mul_f32 v[124:125], v[48:49], v[124:125]
	v_cvt_pk_bf16_f32 v124, v124, v125
	global_store_dword v[58:59], v124, off offset:1024
	v_pk_mul_f32 v[126:127], v[126:127], v[170:171] op_sel_hi:[1,0]
	v_pk_mul_f32 v[126:127], v[50:51], v[126:127]
	v_cvt_pk_bf16_f32 v126, v126, v127
	global_store_dword v[58:59], v126, off offset:1280
	v_pk_mul_f32 v[128:129], v[128:129], v[170:171] op_sel_hi:[1,0]
	v_pk_mul_f32 v[128:129], v[52:53], v[128:129]
	v_cvt_pk_bf16_f32 v128, v128, v129
	global_store_dword v[58:59], v128, off offset:1536
	v_pk_mul_f32 v[130:131], v[130:131], v[170:171] op_sel_hi:[1,0]
	v_pk_mul_f32 v[130:131], v[54:55], v[130:131]
	v_cvt_pk_bf16_f32 v130, v130, v131
	global_store_dword v[58:59], v130, off offset:1792
	ds_read_b32 v116, v56 offset:12
	ds_read_b32 v117, v56 offset:144
	ds_read_b32 v118, v56 offset:16908
	ds_read_b32 v119, v56 offset:17040
	ds_read_b32 v120, v56 offset:33804
	ds_read_b32 v121, v56 offset:33936
	ds_read_b32 v122, v56 offset:50700
	ds_read_b32 v123, v56 offset:50832
	ds_read_b32 v124, v57 offset:12
	ds_read_b32 v125, v57 offset:144
	ds_read_b32 v126, v57 offset:16908
	ds_read_b32 v127, v57 offset:17040
	ds_read_b32 v128, v57 offset:33804
	ds_read_b32 v129, v57 offset:33936
	ds_read_b32 v130, v57 offset:50700
	ds_read_b32 v131, v57 offset:50832
	s_waitcnt lgkmcnt(15)
	v_lshlrev_b32_e32 v132, 16, v100
	v_lshlrev_b32_e32 v133, 16, v101
	v_and_b32_e32 v100, 0xffff0000, v100
	v_and_b32_e32 v101, 0xffff0000, v101
	v_lshlrev_b32_e32 v134, 16, v102
	v_lshlrev_b32_e32 v135, 16, v103
	v_and_b32_e32 v102, 0xffff0000, v102
	v_and_b32_e32 v103, 0xffff0000, v103
	v_lshlrev_b32_e32 v136, 16, v104
	v_lshlrev_b32_e32 v137, 16, v105
	v_and_b32_e32 v104, 0xffff0000, v104
	v_and_b32_e32 v105, 0xffff0000, v105
	v_lshlrev_b32_e32 v138, 16, v106
	v_lshlrev_b32_e32 v139, 16, v107
	v_and_b32_e32 v106, 0xffff0000, v106
	v_and_b32_e32 v107, 0xffff0000, v107
	v_lshlrev_b32_e32 v140, 16, v108
	v_lshlrev_b32_e32 v141, 16, v109
	v_and_b32_e32 v108, 0xffff0000, v108
	v_and_b32_e32 v109, 0xffff0000, v109
	v_lshlrev_b32_e32 v142, 16, v110
	v_lshlrev_b32_e32 v143, 16, v111
	v_and_b32_e32 v110, 0xffff0000, v110
	v_and_b32_e32 v111, 0xffff0000, v111
	v_lshlrev_b32_e32 v144, 16, v112
	v_lshlrev_b32_e32 v145, 16, v113
	v_and_b32_e32 v112, 0xffff0000, v112
	v_and_b32_e32 v113, 0xffff0000, v113
	v_lshlrev_b32_e32 v146, 16, v114
	v_lshlrev_b32_e32 v147, 16, v115
	v_and_b32_e32 v114, 0xffff0000, v114
	v_and_b32_e32 v115, 0xffff0000, v115
	v_pk_mul_f32 v[152:153], v[132:133], v[132:133]
	v_pk_mul_f32 v[154:155], v[140:141], v[140:141]
	v_pk_mul_f32 v[156:157], v[100:101], v[100:101]
	v_pk_mul_f32 v[158:159], v[108:109], v[108:109]
	v_pk_fma_f32 v[152:153], v[134:135], v[134:135], v[152:153]
	v_pk_fma_f32 v[154:155], v[142:143], v[142:143], v[154:155]
	v_pk_fma_f32 v[156:157], v[102:103], v[102:103], v[156:157]
	v_pk_fma_f32 v[158:159], v[110:111], v[110:111], v[158:159]
	v_pk_fma_f32 v[152:153], v[136:137], v[136:137], v[152:153]
	v_pk_fma_f32 v[154:155], v[144:145], v[144:145], v[154:155]
	v_pk_fma_f32 v[156:157], v[104:105], v[104:105], v[156:157]
	v_pk_fma_f32 v[158:159], v[112:113], v[112:113], v[158:159]
	v_pk_fma_f32 v[152:153], v[138:139], v[138:139], v[152:153]
	v_pk_fma_f32 v[154:155], v[146:147], v[146:147], v[154:155]
	v_pk_fma_f32 v[156:157], v[106:107], v[106:107], v[156:157]
	v_pk_fma_f32 v[158:159], v[114:115], v[114:115], v[158:159]
	v_add_f32_e32 v148, v152, v153
	v_add_f32_e32 v149, v154, v155
	v_add_f32_e32 v150, v156, v157
	v_add_f32_e32 v151, v158, v159
	v_add_u32_e32 v61, 0x2000, v60
	s_nop 0
	v_add_f32_dpp v160, v148, v148 quad_perm:[1,0,3,2] row_mask:0xf bank_mask:0xf
	v_add_f32_dpp v161, v149, v149 quad_perm:[1,0,3,2] row_mask:0xf bank_mask:0xf
	v_add_f32_dpp v162, v150, v150 quad_perm:[1,0,3,2] row_mask:0xf bank_mask:0xf
	v_add_f32_dpp v163, v151, v151 quad_perm:[1,0,3,2] row_mask:0xf bank_mask:0xf
	s_nop 0
	v_add_f32_dpp v148, v160, v160 quad_perm:[2,3,0,1] row_mask:0xf bank_mask:0xf
	v_add_f32_dpp v149, v161, v161 quad_perm:[2,3,0,1] row_mask:0xf bank_mask:0xf
	v_add_f32_dpp v150, v162, v162 quad_perm:[2,3,0,1] row_mask:0xf bank_mask:0xf
	v_add_f32_dpp v151, v163, v163 quad_perm:[2,3,0,1] row_mask:0xf bank_mask:0xf
	s_nop 0
	v_add_f32_dpp v160, v148, v148 row_ror:4 row_mask:0xf bank_mask:0xf
	v_add_f32_dpp v161, v149, v149 row_ror:4 row_mask:0xf bank_mask:0xf
	v_add_f32_dpp v162, v150, v150 row_ror:4 row_mask:0xf bank_mask:0xf
	v_add_f32_dpp v163, v151, v151 row_ror:4 row_mask:0xf bank_mask:0xf
	s_nop 0
	v_add_f32_dpp v148, v160, v160 row_ror:8 row_mask:0xf bank_mask:0xf
	v_add_f32_dpp v149, v161, v161 row_ror:8 row_mask:0xf bank_mask:0xf
	v_add_f32_dpp v150, v162, v162 row_ror:8 row_mask:0xf bank_mask:0xf
	v_add_f32_dpp v151, v163, v163 row_ror:8 row_mask:0xf bank_mask:0xf
	ds_bpermute_b32 v160, v74, v148
	ds_bpermute_b32 v161, v74, v149
	ds_bpermute_b32 v162, v74, v150
	ds_bpermute_b32 v163, v74, v151
	s_waitcnt lgkmcnt(0)
	v_add_f32_e32 v148, v148, v160
	v_add_f32_e32 v149, v149, v161
	v_add_f32_e32 v150, v150, v162
	v_add_f32_e32 v151, v151, v163
	ds_bpermute_b32 v160, v73, v148
	ds_bpermute_b32 v161, v73, v149
	ds_bpermute_b32 v162, v73, v150
	ds_bpermute_b32 v163, v73, v151
	s_waitcnt lgkmcnt(0)
	v_add_f32_e32 v148, v148, v160
	v_add_f32_e32 v149, v149, v161
	v_add_f32_e32 v150, v150, v162
	v_add_f32_e32 v151, v151, v163
	v_fma_f32 v148, v148, s4, v178
	v_fma_f32 v149, v149, s4, v178
	v_fma_f32 v150, v150, s4, v178
	v_fma_f32 v151, v151, s4, v178
	v_rsq_f32_e32 v164, v148
	v_rsq_f32_e32 v166, v149
	v_rsq_f32_e32 v168, v150
	v_rsq_f32_e32 v170, v151
	v_add_co_u32_e32 v58, vcc, v61, v38
	s_nop 1
	v_addc_co_u32_e32 v59, vcc, 0, v39, vcc
	v_pk_mul_f32 v[132:133], v[132:133], v[164:165] op_sel_hi:[1,0]
	v_pk_mul_f32 v[132:133], v[40:41], v[132:133]
	v_cvt_pk_bf16_f32 v132, v132, v133
	global_store_dword v[58:59], v132, off
	v_pk_mul_f32 v[134:135], v[134:135], v[164:165] op_sel_hi:[1,0]
	v_pk_mul_f32 v[134:135], v[42:43], v[134:135]
	v_cvt_pk_bf16_f32 v134, v134, v135
	global_store_dword v[58:59], v134, off offset:256
	v_pk_mul_f32 v[136:137], v[136:137], v[164:165] op_sel_hi:[1,0]
	v_pk_mul_f32 v[136:137], v[44:45], v[136:137]
	v_cvt_pk_bf16_f32 v136, v136, v137
	global_store_dword v[58:59], v136, off offset:512
	v_pk_mul_f32 v[138:139], v[138:139], v[164:165] op_sel_hi:[1,0]
	v_pk_mul_f32 v[138:139], v[46:47], v[138:139]
	v_cvt_pk_bf16_f32 v138, v138, v139
	global_store_dword v[58:59], v138, off offset:768
	v_pk_mul_f32 v[140:141], v[140:141], v[166:167] op_sel_hi:[1,0]
	v_pk_mul_f32 v[140:141], v[48:49], v[140:141]
	v_cvt_pk_bf16_f32 v140, v140, v141
	global_store_dword v[58:59], v140, off offset:1024
	v_pk_mul_f32 v[142:143], v[142:143], v[166:167] op_sel_hi:[1,0]
	v_pk_mul_f32 v[142:143], v[50:51], v[142:143]
	v_cvt_pk_bf16_f32 v142, v142, v143
	global_store_dword v[58:59], v142, off offset:1280
	v_pk_mul_f32 v[144:145], v[144:145], v[166:167] op_sel_hi:[1,0]
	v_pk_mul_f32 v[144:145], v[52:53], v[144:145]
	v_cvt_pk_bf16_f32 v144, v144, v145
	global_store_dword v[58:59], v144, off offset:1536
	v_pk_mul_f32 v[146:147], v[146:147], v[166:167] op_sel_hi:[1,0]
	v_pk_mul_f32 v[146:147], v[54:55], v[146:147]
	v_cvt_pk_bf16_f32 v146, v146, v147
	global_store_dword v[58:59], v146, off offset:1792
	v_add_u32_e32 v61, 0x800, v61
	v_add_co_u32_e32 v58, vcc, v61, v38
	s_nop 1
	v_addc_co_u32_e32 v59, vcc, 0, v39, vcc
	v_pk_mul_f32 v[100:101], v[100:101], v[168:169] op_sel_hi:[1,0]
	v_pk_mul_f32 v[100:101], v[40:41], v[100:101]
	v_cvt_pk_bf16_f32 v100, v100, v101
	global_store_dword v[58:59], v100, off
	v_pk_mul_f32 v[102:103], v[102:103], v[168:169] op_sel_hi:[1,0]
	v_pk_mul_f32 v[102:103], v[42:43], v[102:103]
	v_cvt_pk_bf16_f32 v102, v102, v103
	global_store_dword v[58:59], v102, off offset:256
	v_pk_mul_f32 v[104:105], v[104:105], v[168:169] op_sel_hi:[1,0]
	v_pk_mul_f32 v[104:105], v[44:45], v[104:105]
	v_cvt_pk_bf16_f32 v104, v104, v105
	global_store_dword v[58:59], v104, off offset:512
	v_pk_mul_f32 v[106:107], v[106:107], v[168:169] op_sel_hi:[1,0]
	v_pk_mul_f32 v[106:107], v[46:47], v[106:107]
	v_cvt_pk_bf16_f32 v106, v106, v107
	global_store_dword v[58:59], v106, off offset:768
	v_pk_mul_f32 v[108:109], v[108:109], v[170:171] op_sel_hi:[1,0]
	v_pk_mul_f32 v[108:109], v[48:49], v[108:109]
	v_cvt_pk_bf16_f32 v108, v108, v109
	global_store_dword v[58:59], v108, off offset:1024
	v_pk_mul_f32 v[110:111], v[110:111], v[170:171] op_sel_hi:[1,0]
	v_pk_mul_f32 v[110:111], v[50:51], v[110:111]
	v_cvt_pk_bf16_f32 v110, v110, v111
	global_store_dword v[58:59], v110, off offset:1280
	v_pk_mul_f32 v[112:113], v[112:113], v[170:171] op_sel_hi:[1,0]
	v_pk_mul_f32 v[112:113], v[52:53], v[112:113]
	v_cvt_pk_bf16_f32 v112, v112, v113
	global_store_dword v[58:59], v112, off offset:1536
	v_pk_mul_f32 v[114:115], v[114:115], v[170:171] op_sel_hi:[1,0]
	v_pk_mul_f32 v[114:115], v[54:55], v[114:115]
	v_cvt_pk_bf16_f32 v114, v114, v115
	global_store_dword v[58:59], v114, off offset:1792
	s_waitcnt lgkmcnt(0)
	v_lshlrev_b32_e32 v132, 16, v116
	v_lshlrev_b32_e32 v133, 16, v117
	v_and_b32_e32 v116, 0xffff0000, v116
	v_and_b32_e32 v117, 0xffff0000, v117
	v_lshlrev_b32_e32 v134, 16, v118
	v_lshlrev_b32_e32 v135, 16, v119
	v_and_b32_e32 v118, 0xffff0000, v118
	v_and_b32_e32 v119, 0xffff0000, v119
	v_lshlrev_b32_e32 v136, 16, v120
	v_lshlrev_b32_e32 v137, 16, v121
	v_and_b32_e32 v120, 0xffff0000, v120
	v_and_b32_e32 v121, 0xffff0000, v121
	v_lshlrev_b32_e32 v138, 16, v122
	v_lshlrev_b32_e32 v139, 16, v123
	v_and_b32_e32 v122, 0xffff0000, v122
	v_and_b32_e32 v123, 0xffff0000, v123
	v_lshlrev_b32_e32 v140, 16, v124
	v_lshlrev_b32_e32 v141, 16, v125
	v_and_b32_e32 v124, 0xffff0000, v124
	v_and_b32_e32 v125, 0xffff0000, v125
	v_lshlrev_b32_e32 v142, 16, v126
	v_lshlrev_b32_e32 v143, 16, v127
	v_and_b32_e32 v126, 0xffff0000, v126
	v_and_b32_e32 v127, 0xffff0000, v127
	v_lshlrev_b32_e32 v144, 16, v128
	v_lshlrev_b32_e32 v145, 16, v129
	v_and_b32_e32 v128, 0xffff0000, v128
	v_and_b32_e32 v129, 0xffff0000, v129
	v_lshlrev_b32_e32 v146, 16, v130
	v_lshlrev_b32_e32 v147, 16, v131
	v_and_b32_e32 v130, 0xffff0000, v130
	v_and_b32_e32 v131, 0xffff0000, v131
	v_pk_mul_f32 v[152:153], v[132:133], v[132:133]
	v_pk_mul_f32 v[154:155], v[140:141], v[140:141]
	v_pk_mul_f32 v[156:157], v[116:117], v[116:117]
	v_pk_mul_f32 v[158:159], v[124:125], v[124:125]
	v_pk_fma_f32 v[152:153], v[134:135], v[134:135], v[152:153]
	v_pk_fma_f32 v[154:155], v[142:143], v[142:143], v[154:155]
	v_pk_fma_f32 v[156:157], v[118:119], v[118:119], v[156:157]
	v_pk_fma_f32 v[158:159], v[126:127], v[126:127], v[158:159]
	v_pk_fma_f32 v[152:153], v[136:137], v[136:137], v[152:153]
	v_pk_fma_f32 v[154:155], v[144:145], v[144:145], v[154:155]
	v_pk_fma_f32 v[156:157], v[120:121], v[120:121], v[156:157]
	v_pk_fma_f32 v[158:159], v[128:129], v[128:129], v[158:159]
	v_pk_fma_f32 v[152:153], v[138:139], v[138:139], v[152:153]
	v_pk_fma_f32 v[154:155], v[146:147], v[146:147], v[154:155]
	v_pk_fma_f32 v[156:157], v[122:123], v[122:123], v[156:157]
	v_pk_fma_f32 v[158:159], v[130:131], v[130:131], v[158:159]
	v_add_f32_e32 v148, v152, v153
	v_add_f32_e32 v149, v154, v155
	v_add_f32_e32 v150, v156, v157
	v_add_f32_e32 v151, v158, v159
	v_add_u32_e32 v61, 0x3000, v60
	s_nop 0
	v_add_f32_dpp v160, v148, v148 quad_perm:[1,0,3,2] row_mask:0xf bank_mask:0xf
	v_add_f32_dpp v161, v149, v149 quad_perm:[1,0,3,2] row_mask:0xf bank_mask:0xf
	v_add_f32_dpp v162, v150, v150 quad_perm:[1,0,3,2] row_mask:0xf bank_mask:0xf
	v_add_f32_dpp v163, v151, v151 quad_perm:[1,0,3,2] row_mask:0xf bank_mask:0xf
	s_nop 0
	v_add_f32_dpp v148, v160, v160 quad_perm:[2,3,0,1] row_mask:0xf bank_mask:0xf
	v_add_f32_dpp v149, v161, v161 quad_perm:[2,3,0,1] row_mask:0xf bank_mask:0xf
	v_add_f32_dpp v150, v162, v162 quad_perm:[2,3,0,1] row_mask:0xf bank_mask:0xf
	v_add_f32_dpp v151, v163, v163 quad_perm:[2,3,0,1] row_mask:0xf bank_mask:0xf
	s_nop 0
	v_add_f32_dpp v160, v148, v148 row_ror:4 row_mask:0xf bank_mask:0xf
	v_add_f32_dpp v161, v149, v149 row_ror:4 row_mask:0xf bank_mask:0xf
	v_add_f32_dpp v162, v150, v150 row_ror:4 row_mask:0xf bank_mask:0xf
	v_add_f32_dpp v163, v151, v151 row_ror:4 row_mask:0xf bank_mask:0xf
	s_nop 0
	v_add_f32_dpp v148, v160, v160 row_ror:8 row_mask:0xf bank_mask:0xf
	v_add_f32_dpp v149, v161, v161 row_ror:8 row_mask:0xf bank_mask:0xf
	v_add_f32_dpp v150, v162, v162 row_ror:8 row_mask:0xf bank_mask:0xf
	v_add_f32_dpp v151, v163, v163 row_ror:8 row_mask:0xf bank_mask:0xf
	ds_bpermute_b32 v160, v74, v148
	ds_bpermute_b32 v161, v74, v149
	ds_bpermute_b32 v162, v74, v150
	ds_bpermute_b32 v163, v74, v151
	s_waitcnt lgkmcnt(0)
	v_add_f32_e32 v148, v148, v160
	v_add_f32_e32 v149, v149, v161
	v_add_f32_e32 v150, v150, v162
	v_add_f32_e32 v151, v151, v163
	ds_bpermute_b32 v160, v73, v148
	ds_bpermute_b32 v161, v73, v149
	ds_bpermute_b32 v162, v73, v150
	ds_bpermute_b32 v163, v73, v151
	s_waitcnt lgkmcnt(0)
	v_add_f32_e32 v148, v148, v160
	v_add_f32_e32 v149, v149, v161
	v_add_f32_e32 v150, v150, v162
	v_add_f32_e32 v151, v151, v163
	v_fma_f32 v148, v148, s4, v178
	v_fma_f32 v149, v149, s4, v178
	v_fma_f32 v150, v150, s4, v178
	v_fma_f32 v151, v151, s4, v178
	v_rsq_f32_e32 v164, v148
	v_rsq_f32_e32 v166, v149
	v_rsq_f32_e32 v168, v150
	v_rsq_f32_e32 v170, v151
	v_add_co_u32_e32 v58, vcc, v61, v38
	s_nop 1
	v_addc_co_u32_e32 v59, vcc, 0, v39, vcc
	v_pk_mul_f32 v[132:133], v[132:133], v[164:165] op_sel_hi:[1,0]
	v_pk_mul_f32 v[132:133], v[40:41], v[132:133]
	v_cvt_pk_bf16_f32 v132, v132, v133
	global_store_dword v[58:59], v132, off
	v_pk_mul_f32 v[134:135], v[134:135], v[164:165] op_sel_hi:[1,0]
	v_pk_mul_f32 v[134:135], v[42:43], v[134:135]
	v_cvt_pk_bf16_f32 v134, v134, v135
	global_store_dword v[58:59], v134, off offset:256
	v_pk_mul_f32 v[136:137], v[136:137], v[164:165] op_sel_hi:[1,0]
	v_pk_mul_f32 v[136:137], v[44:45], v[136:137]
	v_cvt_pk_bf16_f32 v136, v136, v137
	global_store_dword v[58:59], v136, off offset:512
	v_pk_mul_f32 v[138:139], v[138:139], v[164:165] op_sel_hi:[1,0]
	v_pk_mul_f32 v[138:139], v[46:47], v[138:139]
	v_cvt_pk_bf16_f32 v138, v138, v139
	global_store_dword v[58:59], v138, off offset:768
	v_pk_mul_f32 v[140:141], v[140:141], v[166:167] op_sel_hi:[1,0]
	v_pk_mul_f32 v[140:141], v[48:49], v[140:141]
	v_cvt_pk_bf16_f32 v140, v140, v141
	global_store_dword v[58:59], v140, off offset:1024
	v_pk_mul_f32 v[142:143], v[142:143], v[166:167] op_sel_hi:[1,0]
	v_pk_mul_f32 v[142:143], v[50:51], v[142:143]
	v_cvt_pk_bf16_f32 v142, v142, v143
	global_store_dword v[58:59], v142, off offset:1280
	v_pk_mul_f32 v[144:145], v[144:145], v[166:167] op_sel_hi:[1,0]
	v_pk_mul_f32 v[144:145], v[52:53], v[144:145]
	v_cvt_pk_bf16_f32 v144, v144, v145
	global_store_dword v[58:59], v144, off offset:1536
	v_pk_mul_f32 v[146:147], v[146:147], v[166:167] op_sel_hi:[1,0]
	v_pk_mul_f32 v[146:147], v[54:55], v[146:147]
	v_cvt_pk_bf16_f32 v146, v146, v147
	global_store_dword v[58:59], v146, off offset:1792
	v_add_u32_e32 v61, 0x800, v61
	v_add_co_u32_e32 v58, vcc, v61, v38
	s_nop 1
	v_addc_co_u32_e32 v59, vcc, 0, v39, vcc
	v_pk_mul_f32 v[116:117], v[116:117], v[168:169] op_sel_hi:[1,0]
	v_pk_mul_f32 v[116:117], v[40:41], v[116:117]
	v_cvt_pk_bf16_f32 v116, v116, v117
	global_store_dword v[58:59], v116, off
	v_pk_mul_f32 v[118:119], v[118:119], v[168:169] op_sel_hi:[1,0]
	v_pk_mul_f32 v[118:119], v[42:43], v[118:119]
	v_cvt_pk_bf16_f32 v118, v118, v119
	global_store_dword v[58:59], v118, off offset:256
	v_pk_mul_f32 v[120:121], v[120:121], v[168:169] op_sel_hi:[1,0]
	v_pk_mul_f32 v[120:121], v[44:45], v[120:121]
	v_cvt_pk_bf16_f32 v120, v120, v121
	global_store_dword v[58:59], v120, off offset:512
	v_pk_mul_f32 v[122:123], v[122:123], v[168:169] op_sel_hi:[1,0]
	v_pk_mul_f32 v[122:123], v[46:47], v[122:123]
	v_cvt_pk_bf16_f32 v122, v122, v123
	global_store_dword v[58:59], v122, off offset:768
	v_pk_mul_f32 v[124:125], v[124:125], v[170:171] op_sel_hi:[1,0]
	v_pk_mul_f32 v[124:125], v[48:49], v[124:125]
	v_cvt_pk_bf16_f32 v124, v124, v125
	global_store_dword v[58:59], v124, off offset:1024
	v_pk_mul_f32 v[126:127], v[126:127], v[170:171] op_sel_hi:[1,0]
	v_pk_mul_f32 v[126:127], v[50:51], v[126:127]
	v_cvt_pk_bf16_f32 v126, v126, v127
	global_store_dword v[58:59], v126, off offset:1280
	v_pk_mul_f32 v[128:129], v[128:129], v[170:171] op_sel_hi:[1,0]
	v_pk_mul_f32 v[128:129], v[52:53], v[128:129]
	v_cvt_pk_bf16_f32 v128, v128, v129
	global_store_dword v[58:59], v128, off offset:1536
	v_pk_mul_f32 v[130:131], v[130:131], v[170:171] op_sel_hi:[1,0]
	v_pk_mul_f32 v[130:131], v[54:55], v[130:131]
	v_cvt_pk_bf16_f32 v130, v130, v131
	global_store_dword v[58:59], v130, off offset:1792
	s_or_b64 exec, exec, s[38:39]
	s_add_i32 s9, s9, s3
	s_add_i32 s7, s7, s6
	s_cmpk_gt_i32 s9, 0x1ff
	s_cbranch_scc0 .LBB0_197
